# default cache policy instead of nt for the finalize phase inputs (R', Yl stores in PRE, state dumps in the scan, and their loads)
# baseline (speedup 1.0000x reference)
.LBB0_134:
	v_mov_b32_e32 v19, v180
	s_lshl_b64 s[40:41], s[68:69], 15
	v_and_b32_e32 v181, 31, v19
	v_ashrrev_i32_e32 v1, 5, v19
	v_or_b32_e32 v18, s43, v181
	v_mul_u32_u24_e32 v2, 0x90, v18
	v_lshlrev_b32_e32 v3, 4, v1
	v_add3_u32 v212, s29, v2, v3
	v_and_b32_e32 v2, 16, v19
	v_lshlrev_b32_e32 v4, 2, v19
	v_lshrrev_b32_e32 v3, 2, v19
	v_and_or_b32 v2, v4, 12, v2
	v_and_b32_e32 v3, 0xffffffb, v3
	v_or_b32_e32 v4, s91, v2
	v_lshlrev_b32_e32 v4, 1, v4
	v_mul_lo_u32 v3, v3, s64
	v_or_b32_e32 v2, s43, v2
	v_add3_u32 v213, s76, v4, v3
	v_add_u32_e32 v3, s76, v3
	v_add_u32_e32 v214, v3, v4
	v_lshl_add_u32 v238, v2, 1, v3
	ds_read_b128 v[2:5], v212
	ds_read_b128 v[182:185], v212 offset:32
	ds_read_b64_tr_b16 v[6:7], v213 offset:36864
	ds_read_b64_tr_b16 v[8:9], v213 offset:37440
	ds_read_b64_tr_b16 v[186:187], v213 offset:39168
	ds_read_b64_tr_b16 v[188:189], v213 offset:39744
	ds_read_b64_tr_b16 v[10:11], v214 offset:18432
	ds_read_b64_tr_b16 v[12:13], v214 offset:19008
	ds_read_b64_tr_b16 v[190:191], v214 offset:20736
	ds_read_b64_tr_b16 v[192:193], v214 offset:21312
	ds_read_b64_tr_b16 v[14:15], v214 offset:27648
	ds_read_b64_tr_b16 v[16:17], v214 offset:28224
	ds_read_b64_tr_b16 v[196:197], v214 offset:29952
	ds_read_b64_tr_b16 v[198:199], v214 offset:30528
	ds_read_b64_tr_b16 v[52:53], v238 offset:18432
	ds_read_b64_tr_b16 v[54:55], v238 offset:19008
	ds_read_b64_tr_b16 v[200:201], v238 offset:20736
	ds_read_b64_tr_b16 v[202:203], v238 offset:21312
	ds_read_b64_tr_b16 v[204:205], v238 offset:27648
	ds_read_b64_tr_b16 v[206:207], v238 offset:28224
	ds_read_b64_tr_b16 v[208:209], v238 offset:29952
	ds_read_b64_tr_b16 v[210:211], v238 offset:30528
	s_waitcnt lgkmcnt(0)
	s_add_u32 s38, s38, s40
	s_addc_u32 s39, s39, s41
	v_mfma_f32_32x32x16_bf16 v[68:83], v[6:9], v[2:5], 0
	v_mfma_f32_32x32x16_bf16 v[84:99], v[14:17], v[2:5], 0
	v_mfma_f32_32x32x16_bf16 v[52:67], v[6:9], v[52:55], 0
	v_mfma_f32_32x32x16_bf16 v[2:17], v[10:13], v[204:207], 0
	v_mfma_f32_32x32x16_bf16 v[2:17], v[190:193], v[208:211], v[2:17]
	v_mfma_f32_32x32x16_bf16 v[68:83], v[186:189], v[182:185], v[68:83]
	v_mfma_f32_32x32x16_bf16 v[84:99], v[196:199], v[182:185], v[84:99]
	v_mfma_f32_32x32x16_bf16 v[52:67], v[186:189], v[200:203], v[52:67]
	ds_read_b128 v[182:185], v212 offset:64
	ds_read_b128 v[186:189], v212 offset:96
	ds_read_b64_tr_b16 v[190:191], v213 offset:41472
	ds_read_b64_tr_b16 v[192:193], v213 offset:42048
	ds_read_b64_tr_b16 v[196:197], v213 offset:43776
	ds_read_b64_tr_b16 v[198:199], v213 offset:44352
	ds_read_b64_tr_b16 v[202:203], v214 offset:23616
	ds_read_b64_tr_b16 v[204:205], v214 offset:32256
	ds_read_b64_tr_b16 v[208:209], v214 offset:25344
	ds_read_b64_tr_b16 v[210:211], v214 offset:25920
	ds_read_b64_tr_b16 v[200:201], v214 offset:23040
	ds_read_b64_tr_b16 v[206:207], v214 offset:32832
	ds_read_b64_tr_b16 v[212:213], v214 offset:34560
	ds_read_b64_tr_b16 v[214:215], v214 offset:35136
	ds_read_b64_tr_b16 v[218:219], v238 offset:23616
	ds_read_b64_tr_b16 v[228:229], v238 offset:32256
	ds_read_b64_tr_b16 v[232:233], v238 offset:25344
	ds_read_b64_tr_b16 v[234:235], v238 offset:25920
	ds_read_b64_tr_b16 v[216:217], v238 offset:23040
	ds_read_b64_tr_b16 v[230:231], v238 offset:32832
	ds_read_b64_tr_b16 v[236:237], v238 offset:34560
	ds_read_b64_tr_b16 v[238:239], v238 offset:35136
	s_waitcnt lgkmcnt(2)
	v_mfma_f32_32x32x16_bf16 v[2:17], v[200:203], v[228:231], v[2:17]
	v_mfma_f32_32x32x16_bf16 v[68:83], v[190:193], v[182:185], v[68:83]
	v_mfma_f32_32x32x16_bf16 v[84:99], v[204:207], v[182:185], v[84:99]
	v_mfma_f32_32x32x16_bf16 v[52:67], v[190:193], v[216:219], v[52:67]
	s_waitcnt lgkmcnt(0)
	v_mfma_f32_32x32x16_bf16 v[2:17], v[208:211], v[236:239], v[2:17]
	v_mfma_f32_32x32x16_bf16 v[68:83], v[196:199], v[186:189], v[68:83]
	v_mfma_f32_32x32x16_bf16 v[84:99], v[212:215], v[186:189], v[84:99]
	v_mfma_f32_32x32x16_bf16 v[52:67], v[196:199], v[232:235], v[52:67]
	v_lshl_add_u32 v190, v1, 2, s91
	v_cmp_eq_u32_e32 vcc, v190, v18
	v_or_b32_e32 v200, 1, v190
	v_or_b32_e32 v192, 3, v190
	v_cndmask_b32_e64 v183, 0, 1.0, vcc
	v_cmp_eq_u32_e32 vcc, v200, v18
	v_or_b32_e32 v193, 2, v190
	v_add_u32_e32 v196, 9, v190
	v_add_u32_e32 v197, 8, v190
	v_add_u32_e32 v198, 11, v190
	v_add_u32_e32 v199, 10, v190
	v_sub_f32_e32 v84, v36, v84
	v_cndmask_b32_e64 v36, 0, 1.0, vcc
	v_lshl_add_u32 v182, v18, 2, s87
	v_sub_f32_e32 v191, v183, v52
	v_lshl_add_u32 v183, v190, 2, s87
	v_lshl_add_u32 v184, v193, 2, s87
	v_lshl_add_u32 v185, v192, 2, s87
	v_lshl_add_u32 v186, v197, 2, s87
	v_lshl_add_u32 v187, v196, 2, s87
	v_lshl_add_u32 v188, v199, 2, s87
	v_lshl_add_u32 v189, v198, 2, s87
	v_sub_f32_e32 v36, v36, v53
	v_pk_add_f32 v[2:3], v[152:153], v[2:3] neg_lo:[0,1] neg_hi:[0,1]
	v_cmp_eq_u32_e32 vcc, v192, v18
	ds_read_b32 v52, v182
	ds_read_b64 v[182:183], v183
	ds_read_b32 v184, v184
	ds_read_b32 v185, v185
	ds_read_b32 v186, v186
	ds_read_b32 v187, v187
	ds_read_b32 v188, v188
	ds_read_b32 v189, v189
	v_pk_add_f32 v[68:69], v[154:155], v[68:69] neg_lo:[0,1] neg_hi:[0,1]
	v_sub_f32_e32 v85, v37, v85
	s_waitcnt lgkmcnt(7)
	v_mul_f32_e32 v154, v36, v52
	s_waitcnt lgkmcnt(6)
	v_pk_mul_f32 v[36:37], v[2:3], v[182:183]
	v_cndmask_b32_e64 v3, 0, 1.0, vcc
	v_cmp_eq_u32_e32 vcc, v193, v18
	v_sub_f32_e32 v89, v41, v89
	v_sub_f32_e32 v88, v40, v88
	v_cndmask_b32_e64 v2, 0, 1.0, vcc
	v_pk_add_f32 v[2:3], v[2:3], v[54:55] neg_lo:[0,1] neg_hi:[0,1]
	v_cmp_eq_u32_e32 vcc, v196, v18
	v_pk_mul_f32 v[40:41], v[2:3], v[52:53] op_sel_hi:[1,0]
	v_pk_add_f32 v[2:3], v[150:151], v[4:5] neg_lo:[0,1] neg_hi:[0,1]
	v_sub_f32_e32 v91, v43, v91
	v_sub_f32_e32 v90, v42, v90
	s_waitcnt lgkmcnt(4)
	v_pk_mul_f32 v[42:43], v[2:3], v[184:185]
	v_cndmask_b32_e64 v3, 0, 1.0, vcc
	v_cmp_eq_u32_e32 vcc, v197, v18
	v_sub_f32_e32 v97, v49, v97
	v_sub_f32_e32 v96, v48, v96
	v_cndmask_b32_e64 v2, 0, 1.0, vcc
	v_pk_add_f32 v[2:3], v[2:3], v[56:57] neg_lo:[0,1] neg_hi:[0,1]
	v_cmp_eq_u32_e32 vcc, v198, v18
	v_pk_mul_f32 v[4:5], v[2:3], v[52:53] op_sel_hi:[1,0]
	v_pk_add_f32 v[2:3], v[166:167], v[6:7] neg_lo:[0,1] neg_hi:[0,1]
	v_sub_f32_e32 v93, v45, v93
	s_waitcnt lgkmcnt(2)
	v_pk_mul_f32 v[6:7], v[2:3], v[186:187]
	v_cndmask_b32_e64 v3, 0, 1.0, vcc
	v_cmp_eq_u32_e32 vcc, v199, v18
	v_sub_f32_e32 v92, v44, v92
	v_pk_add_f32 v[44:45], v[164:165], v[72:73] neg_lo:[0,1] neg_hi:[0,1]
	v_cndmask_b32_e64 v2, 0, 1.0, vcc
	v_pk_add_f32 v[2:3], v[2:3], v[58:59] neg_lo:[0,1] neg_hi:[0,1]
	v_add_u32_e32 v72, 26, v190
	v_pk_mul_f32 v[48:49], v[2:3], v[52:53] op_sel_hi:[1,0]
	v_pk_add_f32 v[2:3], v[156:157], v[8:9] neg_lo:[0,1] neg_hi:[0,1]
	v_add_u32_e32 v53, 16, v190
	s_waitcnt lgkmcnt(0)
	v_pk_mul_f32 v[8:9], v[2:3], v[188:189]
	v_add_u32_e32 v2, 17, v190
	v_cmp_eq_u32_e32 vcc, v2, v18
	v_lshl_add_u32 v56, v53, 2, s87
	v_mul_f32_e32 v191, v191, v52
	v_cndmask_b32_e64 v3, 0, 1.0, vcc
	v_cmp_eq_u32_e32 vcc, v53, v18
	v_cvt_pk_f16_f32 v4, v4, v5
	v_cvt_pk_f16_f32 v5, v48, v49
	v_cndmask_b32_e64 v2, 0, 1.0, vcc
	v_pk_add_f32 v[2:3], v[2:3], v[60:61] neg_lo:[0,1] neg_hi:[0,1]
	v_add_u32_e32 v61, 24, v190
	v_pk_mul_f32 v[54:55], v[2:3], v[52:53] op_sel_hi:[1,0]
	v_pk_add_f32 v[2:3], v[170:171], v[10:11] neg_lo:[0,1] neg_hi:[0,1]
	ds_read_b64 v[10:11], v56
	v_add_u32_e32 v53, 18, v190
	v_lshl_add_u32 v56, v53, 2, s87
	v_lshl_add_u32 v58, v61, 2, s87
	v_lshl_add_u32 v60, v72, 2, s87
	s_waitcnt lgkmcnt(0)
	v_pk_mul_f32 v[10:11], v[2:3], v[10:11]
	v_add_u32_e32 v2, 19, v190
	v_cmp_eq_u32_e32 vcc, v2, v18
	ds_read_b64 v[56:57], v56
	ds_read_b64 v[58:59], v58
	ds_read_b32 v60, v60
	v_cndmask_b32_e64 v3, 0, 1.0, vcc
	v_cmp_eq_u32_e32 vcc, v53, v18
	v_sub_f32_e32 v87, v39, v87
	v_sub_f32_e32 v86, v38, v86
	v_cndmask_b32_e64 v2, 0, 1.0, vcc
	v_pk_add_f32 v[2:3], v[2:3], v[62:63] neg_lo:[0,1] neg_hi:[0,1]
	v_pk_add_f32 v[38:39], v[148:149], v[70:71] neg_lo:[0,1] neg_hi:[0,1]
	v_pk_mul_f32 v[62:63], v[2:3], v[52:53] op_sel_hi:[1,0]
	v_pk_add_f32 v[2:3], v[162:163], v[12:13] neg_lo:[0,1] neg_hi:[0,1]
	s_add_u32 s40, s38, 0x2000
	s_waitcnt lgkmcnt(2)
	v_pk_mul_f32 v[12:13], v[2:3], v[56:57]
	v_add_u32_e32 v2, 25, v190
	v_cmp_eq_u32_e32 vcc, v2, v18
	v_sub_f32_e32 v95, v47, v95
	v_sub_f32_e32 v94, v46, v94
	v_cndmask_b32_e64 v3, 0, 1.0, vcc
	v_cmp_eq_u32_e32 vcc, v61, v18
	v_pk_add_f32 v[46:47], v[158:159], v[74:75] neg_lo:[0,1] neg_hi:[0,1]
	s_addc_u32 s41, s39, 0
	v_cndmask_b32_e64 v2, 0, 1.0, vcc
	v_pk_add_f32 v[2:3], v[2:3], v[64:65] neg_lo:[0,1] neg_hi:[0,1]
	v_sub_f32_e32 v99, v51, v99
	v_pk_mul_f32 v[64:65], v[2:3], v[52:53] op_sel_hi:[1,0]
	v_pk_add_f32 v[2:3], v[178:179], v[14:15] neg_lo:[0,1] neg_hi:[0,1]
	v_sub_f32_e32 v98, v50, v98
	s_waitcnt lgkmcnt(1)
	v_pk_mul_f32 v[14:15], v[2:3], v[58:59]
	v_add_u32_e32 v2, 27, v190
	v_cmp_eq_u32_e32 vcc, v2, v18
	v_lshl_add_u32 v2, v2, 2, s87
	ds_read_b32 v61, v2
	v_cndmask_b32_e64 v3, 0, 1.0, vcc
	v_cmp_eq_u32_e32 vcc, v72, v18
	v_pk_add_f32 v[50:51], v[174:175], v[76:77] neg_lo:[0,1] neg_hi:[0,1]
	v_pk_add_f32 v[70:71], v[160:161], v[78:79] neg_lo:[0,1] neg_hi:[0,1]
	v_cndmask_b32_e64 v2, 0, 1.0, vcc
	v_pk_add_f32 v[2:3], v[2:3], v[66:67] neg_lo:[0,1] neg_hi:[0,1]
	v_pk_add_f32 v[56:57], v[176:177], v[80:81] neg_lo:[0,1] neg_hi:[0,1]
	v_pk_mul_f32 v[52:53], v[2:3], v[52:53] op_sel_hi:[1,0]
	v_pk_add_f32 v[2:3], v[168:169], v[16:17] neg_lo:[0,1] neg_hi:[0,1]
	v_pk_add_f32 v[58:59], v[172:173], v[82:83] neg_lo:[0,1] neg_hi:[0,1]
	s_waitcnt lgkmcnt(0)
	v_pk_mul_f32 v[16:17], v[2:3], v[60:61]
	v_lshlrev_b32_e32 v60, 3, v19
	v_bitop3_b32 v2, v181, 63, s43 bitop3:0x36
	v_cvt_pk_f16_f32 v3, v40, v41
	v_add_u32_e32 v40, s66, v60
	v_cndmask_b32_e64 v2, v2, v18, s[36:37]
	v_ashrrev_i32_e32 v41, 31, v40
	v_lshlrev_b32_e32 v61, 1, v2
	v_bfi_b32 v19, 31, v2, v19
	v_cvt_pk_f16_f32 v2, v191, v154
	v_lshl_add_u64 v[40:41], v[40:41], 1, s[38:39]
	global_store_dwordx4 v[40:41], v[2:5], off nt
	v_and_or_b32 v40, v61, 64, s3
	v_lshlrev_b32_e32 v1, 3, v1
	v_cvt_pk_f16_f32 v3, v38, v39
	v_add_lshl_u32 v38, v40, v19, 3
	v_ashrrev_i32_e32 v39, 31, v38
	v_cvt_pk_f16_f32 v2, v68, v69
	v_cvt_pk_f16_f32 v4, v44, v45
	v_cvt_pk_f16_f32 v5, v46, v47
	v_lshl_add_u64 v[38:39], v[38:39], 1, s[40:41]
	global_store_dwordx4 v[38:39], v[2:5], off
	v_add_u32_e32 v38, s25, v60
	v_ashrrev_i32_e32 v39, 31, v38
	v_cvt_pk_f16_f32 v2, v54, v55
	v_cvt_pk_f16_f32 v3, v62, v63
	v_cvt_pk_f16_f32 v4, v64, v65
	v_cvt_pk_f16_f32 v5, v52, v53
	v_lshl_add_u64 v[38:39], v[38:39], 1, s[38:39]
	global_store_dwordx4 v[38:39], v[2:5], off nt
	v_or_b32_e32 v38, 0x80, v40
	v_add_lshl_u32 v38, v38, v19, 3
	v_ashrrev_i32_e32 v39, 31, v38
	v_cvt_pk_f16_f32 v2, v50, v51
	v_cvt_pk_f16_f32 v3, v70, v71
	v_cvt_pk_f16_f32 v4, v56, v57
	v_cvt_pk_f16_f32 v5, v58, v59
	v_lshl_add_u64 v[38:39], v[38:39], 1, s[40:41]
	global_store_dwordx4 v[38:39], v[2:5], off
	s_nop 1
	v_mov_b32_e32 v2, s76
	v_mad_u32_u24 v2, v18, s64, v2
	v_add3_u32 v1, v2, v1, s28
	v_cvt_pk_f16_f32 v2, v84, v85
	v_cvt_pk_f16_f32 v3, v86, v87
	v_cvt_pk_f16_f32 v4, v88, v89
	v_cvt_pk_f16_f32 v5, v90, v91
	ds_write2_b64 v1, v[2:3], v[4:5] offset1:2
	v_cvt_pk_f16_f32 v2, v92, v93
	v_cvt_pk_f16_f32 v3, v94, v95
	v_cvt_pk_f16_f32 v4, v96, v97
	v_cvt_pk_f16_f32 v5, v98, v99
	ds_write2_b64 v1, v[2:3], v[4:5] offset0:4 offset1:6
	v_cvt_pk_f16_f32 v2, v36, v37
	v_cvt_pk_f16_f32 v3, v42, v43
	v_cvt_pk_f16_f32 v4, v6, v7
	v_cvt_pk_f16_f32 v5, v8, v9
	v_add_u32_e32 v1, 0xd800, v1
	ds_write2_b64 v1, v[2:3], v[4:5] offset1:2
	v_cvt_pk_f16_f32 v2, v10, v11
	v_cvt_pk_f16_f32 v3, v12, v13
	v_cvt_pk_f16_f32 v4, v14, v15
	v_cvt_pk_f16_f32 v5, v16, v17
	ds_write2_b64 v1, v[2:3], v[4:5] offset0:4 offset1:6
	v_mov_b32_e32 v18, v180
	s_waitcnt lgkmcnt(0)
	s_barrier
	s_nop 0
	v_and_b32_e32 v2, 16, v18
	v_lshlrev_b32_e32 v4, 2, v18
	v_lshrrev_b32_e32 v3, 2, v18
	v_and_or_b32 v19, v4, 12, v2
	v_and_b32_e32 v3, 0xffffffb, v3
	v_or_b32_e32 v2, s43, v19
	v_or_b32_e32 v19, s91, v19
	v_lshlrev_b32_e32 v2, 1, v2
	v_mul_lo_u32 v36, v3, s64
	v_lshlrev_b32_e32 v19, 1, v19
	v_add3_u32 v16, s76, v2, v36
	v_add3_u32 v19, s76, v19, v36
	ds_read_b64_tr_b16 v[2:3], v16 offset:9216
	ds_read_b64_tr_b16 v[4:5], v16 offset:9792
	ds_read_b64_tr_b16 v[6:7], v16 offset:11520
	ds_read_b64_tr_b16 v[8:9], v16 offset:12096
	ds_read_b64_tr_b16 v[10:11], v16 offset:13824
	ds_read_b64_tr_b16 v[12:13], v16 offset:14400
	ds_read_b64_tr_b16 v[14:15], v16 offset:16128
	ds_read_b64_tr_b16 v[16:17], v16 offset:16704
	ds_read_b64_tr_b16 v[36:37], v19 offset:55296
	ds_read_b64_tr_b16 v[38:39], v19 offset:55872
	ds_read_b64_tr_b16 v[52:53], v19 offset:57600
	ds_read_b64_tr_b16 v[54:55], v19 offset:58176
	ds_read_b64_tr_b16 v[56:57], v19 offset:59904
	ds_read_b64_tr_b16 v[58:59], v19 offset:60480
	ds_read_b64_tr_b16 v[60:61], v19 offset:62208
	ds_read_b64_tr_b16 v[62:63], v19 offset:62784
	ds_read_b64_tr_b16 v[64:65], v19 offset:9216
	ds_read_b64_tr_b16 v[66:67], v19 offset:9792
	ds_read_b64_tr_b16 v[68:69], v19 offset:11520
	ds_read_b64_tr_b16 v[70:71], v19 offset:12096
	ds_read_b64_tr_b16 v[72:73], v19 offset:13824
	ds_read_b64_tr_b16 v[74:75], v19 offset:14400
	ds_read_b64_tr_b16 v[76:77], v19 offset:16128
	ds_read_b64_tr_b16 v[78:79], v19 offset:16704
	v_ashrrev_i32_e32 v1, 5, v18
	v_and_or_b32 v18, v18, 31, s43
	v_mul_u32_u24_e32 v19, 0x90, v18
	v_lshlrev_b32_e32 v96, 4, v1
	v_add3_u32 v19, s76, v19, v96
	ds_read_b128 v[80:83], v19
	ds_read_b128 v[84:87], v19 offset:32
	ds_read_b128 v[88:91], v19 offset:64
	ds_read_b128 v[92:95], v19 offset:96
	s_waitcnt lgkmcnt(14)
	v_mfma_f32_32x32x16_f16 v[36:51], v[36:39], v[2:5], 0
	v_mfma_f32_32x32x16_f16 v[36:51], v[52:55], v[6:9], v[36:51]
	v_mfma_f32_32x32x16_f16 v[36:51], v[56:59], v[10:13], v[36:51]
	s_waitcnt lgkmcnt(12)
	v_mfma_f32_32x32x16_f16 v[36:51], v[60:63], v[14:17], v[36:51]
	s_waitcnt lgkmcnt(3)
	v_mfma_f32_32x32x16_f16 v[2:17], v[64:67], v[80:83], 0
	s_nop 9
	v_cvt_pk_f16_f32 v36, v36, v37
	v_cvt_pk_f16_f32 v37, v38, v39
	v_cvt_pk_f16_f32 v38, v40, v41
	v_or_b32_e32 v40, s28, v18
	v_lshl_add_u32 v18, v40, 5, v96
	v_ashrrev_i32_e32 v19, 31, v18
	v_lshl_add_u64 v[18:19], v[18:19], 1, s[38:39]
	s_waitcnt lgkmcnt(2)
	v_mfma_f32_32x32x16_f16 v[2:17], v[68:71], v[84:87], v[2:17]
	s_mov_b64 s[38:39], 0x4000
	v_cvt_pk_f16_f32 v39, v42, v43
	v_cvt_pk_f16_f32 v43, v46, v47
	v_lshl_add_u64 v[46:47], v[18:19], 0, s[38:39]
	s_movk_i32 s38, 0x4000
	v_cvt_pk_f16_f32 v42, v44, v45
	v_cvt_pk_f16_f32 v44, v48, v49
	s_waitcnt lgkmcnt(1)
	v_mfma_f32_32x32x16_f16 v[2:17], v[72:75], v[88:91], v[2:17]
	v_add_co_u32_e32 v48, vcc, s38, v18
	v_cvt_pk_f16_f32 v45, v50, v51
	s_nop 0
	v_addc_co_u32_e32 v49, vcc, 0, v19, vcc
	global_store_dwordx4 v[48:49], v[36:39], off nt
	global_store_dwordx4 v[46:47], v[42:45], off offset:16 nt
	s_andn2_b64 vcc, exec, s[60:61]
	s_waitcnt lgkmcnt(0)
	v_mfma_f32_32x32x16_f16 v[2:17], v[76:79], v[92:95], v[2:17]
	s_mov_b64 s[38:39], -1
	s_nop 10
	v_cvt_pk_f16_f32 v36, v2, v3
	v_cvt_pk_f16_f32 v37, v4, v5
	v_cvt_pk_f16_f32 v38, v6, v7
	v_cvt_pk_f16_f32 v39, v8, v9
	v_cvt_pk_f16_f32 v2, v10, v11
	v_cvt_pk_f16_f32 v3, v12, v13
	v_cvt_pk_f16_f32 v4, v14, v15
	v_cvt_pk_f16_f32 v5, v16, v17
	s_cbranch_vccnz .LBB0_136
	v_lshlrev_b32_e32 v6, 1, v40
	s_movk_i32 s38, 0x7e
	v_xad_u32 v1, v6, s38, v1
	v_lshl_add_u32 v1, v1, 5, 0
	v_add_u32_e32 v1, 0x14400, v1
	s_mov_b64 s[38:39], 0
	ds_write_b128 v1, v[36:39]
	ds_write_b128 v1, v[2:5] offset:16

.LBB0_138:
	s_waitcnt lgkmcnt(0)
	s_barrier
	s_andn2_b64 vcc, exec, s[36:37]
	s_cbranch_vccnz .LBB0_80
	v_mov_b32_e32 v1, v180
	v_readlane_b32 s38, v255, 17
	v_and_b32_e32 v8, 0xffffffe0, v1
	s_nop 0
	v_and_or_b32 v1, v1, 31, s38
	v_lshlrev_b32_e32 v1, 6, v1
	s_add_i32 s38, 0, 0x14400
	v_add3_u32 v1, s38, v1, v8
	ds_read_b128 v[8:11], v1
	ds_read_b128 v[12:15], v1 offset:16
	s_waitcnt lgkmcnt(1)
	v_pk_add_f16 v8, v36, v8
	v_pk_add_f16 v9, v37, v9
	v_pk_add_f16 v10, v38, v10
	v_pk_add_f16 v11, v39, v11
	s_waitcnt lgkmcnt(0)
	v_pk_add_f16 v2, v2, v12
	v_pk_add_f16 v3, v3, v13
	v_pk_add_f16 v4, v4, v14
	v_pk_add_f16 v5, v5, v15
	global_store_dwordx4 v[6:7], v[8:11], off
	global_store_dwordx4 v[6:7], v[2:5], off offset:16
	s_branch .LBB0_80

.LBB0_472:
	s_lshl_b64 s[28:29], s[38:39], 15
	s_waitcnt lgkmcnt(0)
	s_add_u32 s3, s36, s28
	v_ashrrev_i32_e32 v152, 5, v150
	s_addc_u32 s37, s37, s29
	s_lshl_b64 s[28:29], s[30:31], 13
	v_and_b32_e32 v151, 31, v150
	v_lshlrev_b32_e32 v153, 4, v152
	s_add_u32 s38, s68, s28
	s_addc_u32 s39, s69, s29
	v_lshl_add_u32 v130, v151, 5, v153
	s_add_u32 s28, s3, 0x6000
	v_add_u32_e32 v2, 0xc00, v130
	s_addc_u32 s29, s37, 0
	v_ashrrev_i32_e32 v3, 31, v2
	v_lshl_add_u64 v[6:7], v[2:3], 1, s[28:29]
	global_load_dwordx4 v[2:5], v[6:7], off offset:16
	s_nop 0
	global_load_dwordx4 v[6:9], v[6:7], off
	v_ashrrev_i32_e32 v131, 31, v130
	v_lshlrev_b64 v[132:133], 1, v[130:131]
	v_lshl_add_u64 v[54:55], s[28:29], 0, v[132:133]
	v_lshlrev_b32_e32 v134, 3, v150
	s_add_u32 s36, s3, 0x2000
	v_lshl_add_u64 v[94:95], s[38:39], 0, v[132:133]
	v_add_u32_e32 v136, 0x200, v134
	v_add_u32_e32 v138, 0x400, v134
	v_add_u32_e32 v140, 0x600, v134
	s_movk_i32 s3, 0x1000
	v_add_u32_e32 v142, 0x800, v134
	s_addc_u32 s37, s37, 0
	v_ashrrev_i32_e32 v135, 31, v134
	v_ashrrev_i32_e32 v137, 31, v136
	v_ashrrev_i32_e32 v139, 31, v138
	v_ashrrev_i32_e32 v141, 31, v140
	v_add_co_u32_e32 v106, vcc, s3, v94
	v_ashrrev_i32_e32 v143, 31, v142
	v_add_u32_e32 v144, 0xa00, v134
	v_lshl_add_u64 v[74:75], v[134:135], 1, s[36:37]
	v_lshl_add_u64 v[78:79], v[136:137], 1, s[36:37]
	v_lshl_add_u64 v[90:91], v[138:139], 1, s[36:37]
	v_lshl_add_u64 v[96:97], v[140:141], 1, s[36:37]
	v_addc_co_u32_e32 v107, vcc, 0, v95, vcc
	v_lshl_add_u64 v[108:109], v[142:143], 1, s[36:37]
	v_ashrrev_i32_e32 v145, 31, v144
	v_add_u32_e32 v146, 0xc00, v134
	v_add_u32_e32 v148, 0xe00, v134
	v_ashrrev_i32_e32 v147, 31, v146
	v_ashrrev_i32_e32 v149, 31, v148
	v_lshl_add_u64 v[122:123], v[146:147], 1, s[36:37]
	v_lshl_add_u64 v[126:127], v[148:149], 1, s[36:37]
	s_waitcnt vmcnt(1)
	v_cvt_f32_f16_e32 v10, v2
	s_waitcnt vmcnt(0)
	v_cvt_f32_f16_e32 v18, v6
	v_cvt_f32_f16_sdwa v19, v6 dst_sel:DWORD dst_unused:UNUSED_PAD src0_sel:WORD_1
	v_cvt_f32_f16_sdwa v11, v2 dst_sel:DWORD dst_unused:UNUSED_PAD src0_sel:WORD_1
	v_cvt_f32_f16_e32 v2, v3
	v_cvt_f32_f16_sdwa v3, v3 dst_sel:DWORD dst_unused:UNUSED_PAD src0_sel:WORD_1
	v_cvt_f32_f16_e32 v12, v4
	v_cvt_f32_f16_sdwa v13, v4 dst_sel:DWORD dst_unused:UNUSED_PAD src0_sel:WORD_1
	v_cvt_f32_f16_e32 v20, v7
	v_cvt_f32_f16_sdwa v21, v7 dst_sel:DWORD dst_unused:UNUSED_PAD src0_sel:WORD_1
	v_cvt_f32_f16_e32 v4, v5
	v_cvt_f32_f16_sdwa v5, v5 dst_sel:DWORD dst_unused:UNUSED_PAD src0_sel:WORD_1
	v_pk_add_f32 v[14:15], v[12:13], 0 op_sel_hi:[1,0]
	v_pk_add_f32 v[12:13], v[2:3], 0 op_sel_hi:[1,0]
	v_pk_add_f32 v[2:3], v[18:19], 0 op_sel_hi:[1,0]
	v_add_u32_e32 v18, 0x400, v130
	v_ashrrev_i32_e32 v19, 31, v18
	v_lshl_add_u64 v[22:23], v[18:19], 1, s[28:29]
	v_pk_add_f32 v[16:17], v[4:5], 0 op_sel_hi:[1,0]
	v_pk_add_f32 v[4:5], v[20:21], 0 op_sel_hi:[1,0]
	global_load_dwordx4 v[18:21], v[22:23], off offset:16
	s_nop 0
	global_load_dwordx4 v[22:25], v[22:23], off
	v_cvt_f32_f16_e32 v6, v8
	v_cvt_f32_f16_sdwa v7, v8 dst_sel:DWORD dst_unused:UNUSED_PAD src0_sel:WORD_1
	v_cvt_f32_f16_e32 v8, v9
	v_cvt_f32_f16_sdwa v9, v9 dst_sel:DWORD dst_unused:UNUSED_PAD src0_sel:WORD_1
	v_pk_add_f32 v[10:11], v[10:11], 0 op_sel_hi:[1,0]
	v_pk_add_f32 v[6:7], v[6:7], 0 op_sel_hi:[1,0]
	v_pk_add_f32 v[8:9], v[8:9], 0 op_sel_hi:[1,0]
	s_waitcnt vmcnt(1)
	v_cvt_f32_f16_e32 v26, v18
	s_waitcnt vmcnt(0)
	v_cvt_f32_f16_e32 v34, v22
	v_cvt_f32_f16_sdwa v35, v22 dst_sel:DWORD dst_unused:UNUSED_PAD src0_sel:WORD_1
	v_cvt_f32_f16_sdwa v27, v18 dst_sel:DWORD dst_unused:UNUSED_PAD src0_sel:WORD_1
	v_cvt_f32_f16_e32 v18, v19
	v_cvt_f32_f16_sdwa v19, v19 dst_sel:DWORD dst_unused:UNUSED_PAD src0_sel:WORD_1
	v_cvt_f32_f16_e32 v28, v20
	v_cvt_f32_f16_sdwa v29, v20 dst_sel:DWORD dst_unused:UNUSED_PAD src0_sel:WORD_1
	v_cvt_f32_f16_e32 v36, v23
	v_cvt_f32_f16_sdwa v37, v23 dst_sel:DWORD dst_unused:UNUSED_PAD src0_sel:WORD_1
	v_cvt_f32_f16_e32 v20, v21
	v_cvt_f32_f16_sdwa v21, v21 dst_sel:DWORD dst_unused:UNUSED_PAD src0_sel:WORD_1
	v_pk_add_f32 v[30:31], v[28:29], 0 op_sel_hi:[1,0]
	v_pk_add_f32 v[28:29], v[18:19], 0 op_sel_hi:[1,0]
	v_pk_add_f32 v[18:19], v[34:35], 0 op_sel_hi:[1,0]
	v_add_u32_e32 v34, 0x800, v130
	v_ashrrev_i32_e32 v35, 31, v34
	v_lshl_add_u64 v[38:39], v[34:35], 1, s[28:29]
	v_pk_add_f32 v[32:33], v[20:21], 0 op_sel_hi:[1,0]
	v_pk_add_f32 v[20:21], v[36:37], 0 op_sel_hi:[1,0]
	global_load_dwordx4 v[34:37], v[38:39], off offset:16
	s_nop 0
	global_load_dwordx4 v[38:41], v[38:39], off
	v_cvt_f32_f16_e32 v22, v24
	v_cvt_f32_f16_sdwa v23, v24 dst_sel:DWORD dst_unused:UNUSED_PAD src0_sel:WORD_1
	v_cvt_f32_f16_e32 v24, v25
	v_cvt_f32_f16_sdwa v25, v25 dst_sel:DWORD dst_unused:UNUSED_PAD src0_sel:WORD_1
	v_pk_add_f32 v[26:27], v[26:27], 0 op_sel_hi:[1,0]
	v_pk_add_f32 v[22:23], v[22:23], 0 op_sel_hi:[1,0]
	v_pk_add_f32 v[24:25], v[24:25], 0 op_sel_hi:[1,0]
	s_waitcnt vmcnt(1)
	v_cvt_f32_f16_e32 v42, v34
	s_waitcnt vmcnt(0)
	v_cvt_f32_f16_e32 v50, v38
	v_cvt_f32_f16_sdwa v51, v38 dst_sel:DWORD dst_unused:UNUSED_PAD src0_sel:WORD_1
	v_cvt_f32_f16_e32 v52, v39
	v_cvt_f32_f16_sdwa v53, v39 dst_sel:DWORD dst_unused:UNUSED_PAD src0_sel:WORD_1
	v_cvt_f32_f16_sdwa v43, v34 dst_sel:DWORD dst_unused:UNUSED_PAD src0_sel:WORD_1
	v_cvt_f32_f16_e32 v34, v35
	v_cvt_f32_f16_sdwa v35, v35 dst_sel:DWORD dst_unused:UNUSED_PAD src0_sel:WORD_1
	v_cvt_f32_f16_e32 v44, v36
	v_cvt_f32_f16_sdwa v45, v36 dst_sel:DWORD dst_unused:UNUSED_PAD src0_sel:WORD_1
	v_cvt_f32_f16_e32 v36, v37
	v_cvt_f32_f16_sdwa v37, v37 dst_sel:DWORD dst_unused:UNUSED_PAD src0_sel:WORD_1
	v_cvt_f32_f16_e32 v38, v40
	v_pk_add_f32 v[46:47], v[44:45], 0 op_sel_hi:[1,0]
	v_pk_add_f32 v[44:45], v[34:35], 0 op_sel_hi:[1,0]
	v_pk_add_f32 v[48:49], v[36:37], 0 op_sel_hi:[1,0]
	v_pk_add_f32 v[36:37], v[52:53], 0 op_sel_hi:[1,0]
	v_pk_add_f32 v[34:35], v[50:51], 0 op_sel_hi:[1,0]
	global_load_dwordx4 v[50:53], v[54:55], off offset:16
	s_nop 0
	global_load_dwordx4 v[54:57], v[54:55], off
	v_cvt_f32_f16_sdwa v39, v40 dst_sel:DWORD dst_unused:UNUSED_PAD src0_sel:WORD_1
	v_cvt_f32_f16_e32 v40, v41
	v_cvt_f32_f16_sdwa v41, v41 dst_sel:DWORD dst_unused:UNUSED_PAD src0_sel:WORD_1
	v_pk_add_f32 v[42:43], v[42:43], 0 op_sel_hi:[1,0]
	v_pk_add_f32 v[38:39], v[38:39], 0 op_sel_hi:[1,0]
	v_pk_add_f32 v[40:41], v[40:41], 0 op_sel_hi:[1,0]
	s_waitcnt vmcnt(1)
	v_cvt_f32_f16_e32 v58, v50
	s_waitcnt vmcnt(0)
	v_cvt_f32_f16_e32 v66, v54
	v_cvt_f32_f16_sdwa v67, v54 dst_sel:DWORD dst_unused:UNUSED_PAD src0_sel:WORD_1
	v_cvt_f32_f16_e32 v68, v55
	v_cvt_f32_f16_sdwa v69, v55 dst_sel:DWORD dst_unused:UNUSED_PAD src0_sel:WORD_1
	v_cvt_f32_f16_sdwa v59, v50 dst_sel:DWORD dst_unused:UNUSED_PAD src0_sel:WORD_1
	v_cvt_f32_f16_e32 v50, v51
	v_cvt_f32_f16_sdwa v51, v51 dst_sel:DWORD dst_unused:UNUSED_PAD src0_sel:WORD_1
	v_cvt_f32_f16_e32 v60, v52
	v_cvt_f32_f16_sdwa v61, v52 dst_sel:DWORD dst_unused:UNUSED_PAD src0_sel:WORD_1
	v_cvt_f32_f16_e32 v52, v53
	v_cvt_f32_f16_sdwa v53, v53 dst_sel:DWORD dst_unused:UNUSED_PAD src0_sel:WORD_1
	v_cvt_f32_f16_e32 v54, v56
	v_pk_add_f32 v[62:63], v[60:61], 0 op_sel_hi:[1,0]
	v_pk_add_f32 v[60:61], v[50:51], 0 op_sel_hi:[1,0]
	v_pk_add_f32 v[64:65], v[52:53], 0 op_sel_hi:[1,0]
	v_pk_add_f32 v[52:53], v[68:69], 0 op_sel_hi:[1,0]
	v_pk_add_f32 v[50:51], v[66:67], 0 op_sel_hi:[1,0]
	global_load_dwordx4 v[70:73], v[94:95], off
	global_load_dwordx4 v[66:69], v[94:95], off offset:2048
	v_cvt_f32_f16_sdwa v55, v56 dst_sel:DWORD dst_unused:UNUSED_PAD src0_sel:WORD_1
	global_load_dwordx4 v[74:77], v[74:75], off
	s_nop 0
	global_load_dwordx4 v[86:89], v[78:79], off
	global_load_dwordx4 v[82:85], v[94:95], off offset:16
	s_nop 0
	global_load_dwordx4 v[78:81], v[94:95], off offset:2064
	global_load_dwordx4 v[102:105], v[96:97], off
	v_cvt_f32_f16_e32 v56, v57
	global_load_dwordx4 v[90:93], v[90:91], off
	s_nop 0
	global_load_dwordx4 v[98:101], v[106:107], off
	global_load_dwordx4 v[94:97], v[106:107], off offset:2048
	global_load_dwordx4 v[110:113], v[108:109], off
	v_lshl_add_u64 v[108:109], v[144:145], 1, s[36:37]
	global_load_dwordx4 v[118:121], v[108:109], off
	global_load_dwordx4 v[114:117], v[106:107], off offset:16
	s_nop 0
	global_load_dwordx4 v[106:109], v[106:107], off offset:2064
	v_cvt_f32_f16_sdwa v57, v57 dst_sel:DWORD dst_unused:UNUSED_PAD src0_sel:WORD_1
	global_load_dwordx4 v[122:125], v[122:123], off
	v_pk_add_f32 v[58:59], v[58:59], 0 op_sel_hi:[1,0]
	global_load_dwordx4 v[126:129], v[126:127], off
	v_pk_add_f32 v[56:57], v[56:57], 0 op_sel_hi:[1,0]
	v_pk_add_f32 v[54:55], v[54:55], 0 op_sel_hi:[1,0]
	s_waitcnt vmcnt(13)
	s_nop 0
	v_mfma_f32_32x32x16_f16 v[50:65], v[70:73], v[74:77], v[50:65]
	s_xor_b32 s30, s30, 0x7f
	s_ashr_i32 s31, s30, 31
	s_cmpk_lt_i32 s30, 0x800
	s_mov_b64 s[38:39], s[30:31]
	s_mov_b64 s[36:37], s[26:27]
	v_mfma_f32_32x32x16_f16 v[34:49], v[66:69], v[74:77], v[34:49]
	s_waitcnt vmcnt(12)
	v_mfma_f32_32x32x16_f16 v[18:33], v[70:73], v[86:89], v[18:33]
	v_mfma_f32_32x32x16_f16 v[2:17], v[66:69], v[86:89], v[2:17]
	s_waitcnt vmcnt(8)
	v_mfma_f32_32x32x16_f16 v[50:65], v[82:85], v[90:93], v[50:65]
	v_mfma_f32_32x32x16_f16 v[34:49], v[78:81], v[90:93], v[34:49]
	v_mfma_f32_32x32x16_f16 v[18:33], v[82:85], v[102:105], v[18:33]
	v_mfma_f32_32x32x16_f16 v[2:17], v[78:81], v[102:105], v[2:17]
	s_waitcnt vmcnt(5)
	v_mfma_f32_32x32x16_f16 v[50:65], v[98:101], v[110:113], v[50:65]
	v_mfma_f32_32x32x16_f16 v[34:49], v[94:97], v[110:113], v[34:49]
	s_waitcnt vmcnt(4)
	v_mfma_f32_32x32x16_f16 v[18:33], v[98:101], v[118:121], v[18:33]
	v_mfma_f32_32x32x16_f16 v[2:17], v[94:97], v[118:121], v[2:17]
	s_waitcnt vmcnt(1)
	v_mfma_f32_32x32x16_f16 v[50:65], v[114:117], v[122:125], v[50:65]
	v_mfma_f32_32x32x16_f16 v[34:49], v[106:109], v[122:125], v[34:49]
	s_waitcnt vmcnt(0)
	v_mfma_f32_32x32x16_f16 v[18:33], v[114:117], v[126:129], v[18:33]
	v_mfma_f32_32x32x16_f16 v[2:17], v[106:109], v[126:129], v[2:17]
	s_cbranch_scc1 .LBB0_451
	v_readlane_b32 s28, v254, 59
	v_readlane_b32 s29, v254, 60
	s_load_dwordx2 s[36:37], s[28:29], 0xa8
	s_add_i32 s50, s30, 0xfffff800
	s_mov_b64 s[38:39], s[50:51]
	s_branch .LBB0_451

.LBB0_629:
	v_lshl_add_u64 v[146:147], s[26:27], 0, v[142:143]
	s_mov_b32 s3, 0x4c00000
	v_add_co_u32_e32 v66, vcc, s3, v146
	s_mov_b32 s3, 0x4c01000
	s_nop 0
	v_addc_co_u32_e32 v67, vcc, 0, v147, vcc
	v_add_co_u32_e32 v68, vcc, s3, v146
	s_add_i32 s1, s0, -6
	v_cvt_pk_f16_f32 v34, v34, v35
	v_cvt_pk_f16_f32 v35, v36, v37
	v_cvt_pk_f16_f32 v36, v38, v39
	v_cvt_pk_f16_f32 v37, v40, v41
	v_addc_co_u32_e32 v69, vcc, 0, v147, vcc
	v_cvt_pk_f16_f32 v38, v42, v43
	v_cvt_pk_f16_f32 v39, v44, v45
	v_cvt_pk_f16_f32 v40, v46, v47
	v_cvt_pk_f16_f32 v41, v48, v49
	v_cvt_pk_f16_f32 v42, v50, v51
	v_cvt_pk_f16_f32 v43, v52, v53
	v_cvt_pk_f16_f32 v44, v54, v55
	v_cvt_pk_f16_f32 v45, v56, v57
	v_cvt_pk_f16_f32 v46, v58, v59
	v_cvt_pk_f16_f32 v47, v60, v61
	v_cvt_pk_f16_f32 v48, v62, v63
	v_cvt_pk_f16_f32 v49, v64, v65
	global_store_dwordx4 v[68:69], v[34:37], off offset:-4096
	global_store_dwordx4 v[66:67], v[38:41], off offset:16
	global_store_dwordx4 v[68:69], v[42:45], off
	global_store_dwordx4 v[68:69], v[46:49], off offset:16
	v_mov_b64_e32 v[96:97], v[16:17]
	v_mov_b64_e32 v[80:81], v[32:33]
	v_mov_b64_e32 v[94:95], v[14:15]
	v_mov_b64_e32 v[92:93], v[12:13]
	v_mov_b64_e32 v[90:91], v[10:11]
	v_mov_b64_e32 v[88:89], v[8:9]
	v_mov_b64_e32 v[86:87], v[6:7]
	v_mov_b64_e32 v[84:85], v[4:5]
	v_mov_b64_e32 v[82:83], v[2:3]
	v_mov_b64_e32 v[78:79], v[30:31]
	v_mov_b64_e32 v[76:77], v[28:29]
	v_mov_b64_e32 v[74:75], v[26:27]
	v_mov_b64_e32 v[72:73], v[24:25]
	v_mov_b64_e32 v[70:71], v[22:23]
	v_mov_b64_e32 v[68:69], v[20:21]
	v_mov_b64_e32 v[66:67], v[18:19]
	v_mfma_f32_32x32x16_f16 v[82:97], v[98:101], v[34:37], v[82:97]
	s_nop 0
	v_mfma_f32_32x32x16_f16 v[66:81], v[114:117], v[34:37], v[66:81]
	v_mfma_f32_32x32x16_f16 v[82:97], v[102:105], v[38:41], v[82:97]
	v_mfma_f32_32x32x16_f16 v[66:81], v[118:121], v[38:41], v[66:81]
	v_mfma_f32_32x32x16_f16 v[82:97], v[106:109], v[42:45], v[82:97]
	v_mfma_f32_32x32x16_f16 v[66:81], v[122:125], v[42:45], v[66:81]
	v_mfma_f32_32x32x16_f16 v[82:97], v[110:113], v[46:49], v[82:97]
	v_mfma_f32_32x32x16_f16 v[66:81], v[126:129], v[46:49], v[66:81]
	s_cmp_gt_u32 s1, 58
	s_cselect_b64 s[30:31], -1, 0
	s_and_b64 vcc, exec, s[30:31]
	v_lshl_add_u64 v[158:159], s[24:25], 0, v[130:131]
	v_lshl_add_u64 v[156:157], s[24:25], 0, v[132:133]
	v_lshl_add_u64 v[154:155], s[24:25], 0, v[134:135]
	v_lshl_add_u64 v[152:153], s[24:25], 0, v[136:137]
	v_lshl_add_u64 v[150:151], s[24:25], 0, v[138:139]
	v_lshl_add_u64 v[148:149], s[24:25], 0, v[142:143]
	v_lshl_add_u64 v[144:145], s[24:25], 0, v[140:141]
	s_cbranch_vccnz .LBB0_640
	s_add_i32 s3, s0, 0xffff
	s_mul_i32 s28, s3, 0xab
	s_bfe_u32 s28, s28, 0x6000a
	s_mul_i32 s28, s28, 6
	s_sub_i32 s3, s3, s28
	s_and_b32 s3, s3, 0xff
	s_mulk_i32 s3, 0x3000
	s_add_i32 s3, s3, 0
	s_mov_b64 s[36:37], 0x28000
	v_lshl_add_u64 v[34:35], v[158:159], 0, s[36:37]
	s_mov_b32 m0, s3
	s_mov_b64 s[28:29], 0x28400
	global_load_lds_dwordx4 v[34:35], off nt
	v_lshl_add_u64 v[34:35], v[158:159], 0, s[28:29]
	s_add_i32 m0, s3, 0x400
	s_mov_b64 s[28:29], 0x28800
	global_load_lds_dwordx4 v[34:35], off nt
	v_lshl_add_u64 v[34:35], v[158:159], 0, s[28:29]
	s_add_i32 m0, s3, 0x800
	s_mov_b64 s[28:29], 0x28c00
	global_load_lds_dwordx4 v[34:35], off nt
	v_lshl_add_u64 v[34:35], v[158:159], 0, s[28:29]
	s_add_i32 m0, s3, 0xc00
	s_mov_b64 s[28:29], 0x2c000
	global_load_lds_dwordx4 v[34:35], off nt
	v_lshl_add_u64 v[34:35], v[156:157], 0, s[36:37]
	s_add_i32 m0, s3, 0x1000
	s_nop 0
	global_load_lds_dwordx4 v[34:35], off nt
	v_lshl_add_u64 v[34:35], v[154:155], 0, s[36:37]
	s_add_i32 m0, s3, 0x1400
	s_nop 0
	global_load_lds_dwordx4 v[34:35], off nt
	v_lshl_add_u64 v[34:35], v[152:153], 0, s[36:37]
	s_add_i32 m0, s3, 0x1800
	s_nop 0
	global_load_lds_dwordx4 v[34:35], off nt
	v_lshl_add_u64 v[34:35], v[150:151], 0, s[36:37]
	s_add_i32 m0, s3, 0x1c00
	s_mov_b64 s[36:37], 0x2c010
	global_load_lds_dwordx4 v[34:35], off nt
	v_lshl_add_u64 v[34:35], v[148:149], 0, s[28:29]
	s_add_i32 m0, s3, 0x2000
	s_nop 0
	global_load_lds_dwordx4 v[34:35], off nt
	v_lshl_add_u64 v[34:35], v[148:149], 0, s[36:37]
	s_add_i32 m0, s3, 0x2400
	s_nop 0
	global_load_lds_dwordx4 v[34:35], off nt
	v_lshl_add_u64 v[34:35], v[144:145], 0, s[28:29]
	s_add_i32 m0, s3, 0x2800
	s_nop 0
	global_load_lds_dwordx4 v[34:35], off nt
	v_lshl_add_u64 v[34:35], v[144:145], 0, s[36:37]
	s_add_i32 m0, s3, 0x2c00
	s_nop 0
	global_load_lds_dwordx4 v[34:35], off nt
	s_mov_b64 s[36:37], -1
	s_and_b64 vcc, exec, s[30:31]
	s_cbranch_vccnz .LBB0_641

.LBB0_633:
	s_add_i32 s3, s0, 0xfffb
	s_mul_i32 s28, s3, 0xab
	s_bfe_u32 s28, s28, 0x6000a
	s_mul_i32 s28, s28, 6
	s_sub_i32 s3, s3, s28
	s_and_b32 s3, s3, 0xff
	s_mulk_i32 s3, 0x3000
	v_add_u32_e32 v188, s3, v1
	ds_read_b128 v[38:41], v188 offset:8192
	ds_read_b128 v[46:49], v188 offset:9216
	ds_read_b128 v[54:57], v188 offset:10240
	ds_read_b128 v[62:65], v188 offset:11264
	ds_read_b128 v[160:163], v188
	ds_read_b128 v[164:167], v188 offset:1024
	ds_read_b128 v[168:171], v188 offset:2048
	ds_read_b128 v[172:175], v188 offset:3072
	ds_read_b128 v[176:179], v188 offset:4096
	ds_read_b128 v[180:183], v188 offset:5120
	ds_read_b128 v[184:187], v188 offset:6144
	ds_read_b128 v[188:191], v188 offset:7168
	s_waitcnt lgkmcnt(0)
	v_cvt_f32_f16_e32 v34, v38
	v_cvt_f32_f16_sdwa v35, v38 dst_sel:DWORD dst_unused:UNUSED_PAD src0_sel:WORD_1
	v_cvt_f32_f16_e32 v42, v46
	v_cvt_f32_f16_sdwa v43, v46 dst_sel:DWORD dst_unused:UNUSED_PAD src0_sel:WORD_1
	v_cvt_f32_f16_e32 v36, v39
	v_cvt_f32_f16_sdwa v37, v39 dst_sel:DWORD dst_unused:UNUSED_PAD src0_sel:WORD_1
	v_cvt_f32_f16_e32 v44, v47
	v_cvt_f32_f16_sdwa v45, v47 dst_sel:DWORD dst_unused:UNUSED_PAD src0_sel:WORD_1
	v_cvt_f32_f16_e32 v38, v40
	v_cvt_f32_f16_sdwa v39, v40 dst_sel:DWORD dst_unused:UNUSED_PAD src0_sel:WORD_1
	v_cvt_f32_f16_e32 v46, v48
	v_cvt_f32_f16_sdwa v47, v48 dst_sel:DWORD dst_unused:UNUSED_PAD src0_sel:WORD_1
	v_cvt_f32_f16_e32 v40, v41
	v_cvt_f32_f16_sdwa v41, v41 dst_sel:DWORD dst_unused:UNUSED_PAD src0_sel:WORD_1
	v_cvt_f32_f16_e32 v48, v49
	v_cvt_f32_f16_sdwa v49, v49 dst_sel:DWORD dst_unused:UNUSED_PAD src0_sel:WORD_1
	v_cvt_f32_f16_e32 v50, v54
	v_cvt_f32_f16_sdwa v51, v54 dst_sel:DWORD dst_unused:UNUSED_PAD src0_sel:WORD_1
	v_cvt_f32_f16_e32 v58, v62
	v_cvt_f32_f16_sdwa v59, v62 dst_sel:DWORD dst_unused:UNUSED_PAD src0_sel:WORD_1
	v_cvt_f32_f16_e32 v52, v55
	v_cvt_f32_f16_sdwa v53, v55 dst_sel:DWORD dst_unused:UNUSED_PAD src0_sel:WORD_1
	v_cvt_f32_f16_e32 v60, v63
	v_cvt_f32_f16_sdwa v61, v63 dst_sel:DWORD dst_unused:UNUSED_PAD src0_sel:WORD_1
	v_cvt_f32_f16_e32 v54, v56
	v_cvt_f32_f16_sdwa v55, v56 dst_sel:DWORD dst_unused:UNUSED_PAD src0_sel:WORD_1
	v_cvt_f32_f16_e32 v62, v64
	v_cvt_f32_f16_sdwa v63, v64 dst_sel:DWORD dst_unused:UNUSED_PAD src0_sel:WORD_1
	v_cvt_f32_f16_e32 v56, v57
	v_cvt_f32_f16_sdwa v57, v57 dst_sel:DWORD dst_unused:UNUSED_PAD src0_sel:WORD_1
	v_cvt_f32_f16_e32 v64, v65
	v_cvt_f32_f16_sdwa v65, v65 dst_sel:DWORD dst_unused:UNUSED_PAD src0_sel:WORD_1
	s_mov_b32 s3, 0x4c02000
	v_add_co_u32_e32 v192, vcc, s3, v146
	s_mov_b32 s3, 0x4c03000
	s_nop 0
	v_addc_co_u32_e32 v193, vcc, 0, v147, vcc
	v_add_co_u32_e32 v146, vcc, s3, v146
	v_cvt_pk_f16_f32 v82, v82, v83
	v_cvt_pk_f16_f32 v83, v84, v85
	v_cvt_pk_f16_f32 v84, v86, v87
	v_cvt_pk_f16_f32 v85, v88, v89
	v_addc_co_u32_e32 v147, vcc, 0, v147, vcc
	v_cvt_pk_f16_f32 v86, v90, v91
	v_cvt_pk_f16_f32 v87, v92, v93
	v_cvt_pk_f16_f32 v88, v94, v95
	v_cvt_pk_f16_f32 v89, v96, v97
	v_cvt_pk_f16_f32 v66, v66, v67
	v_cvt_pk_f16_f32 v67, v68, v69
	v_cvt_pk_f16_f32 v68, v70, v71
	v_cvt_pk_f16_f32 v69, v72, v73
	v_cvt_pk_f16_f32 v70, v74, v75
	v_cvt_pk_f16_f32 v71, v76, v77
	v_cvt_pk_f16_f32 v72, v78, v79
	v_cvt_pk_f16_f32 v73, v80, v81
	global_store_dwordx4 v[146:147], v[82:85], off offset:-4096
	global_store_dwordx4 v[192:193], v[86:89], off offset:16
	global_store_dwordx4 v[146:147], v[66:69], off
	global_store_dwordx4 v[146:147], v[70:73], off offset:16
	v_mfma_f32_32x32x16_f16 v[34:49], v[160:163], v[82:85], v[34:49]
	v_mfma_f32_32x32x16_f16 v[50:65], v[176:179], v[82:85], v[50:65]
	v_mfma_f32_32x32x16_f16 v[34:49], v[164:167], v[86:89], v[34:49]
	v_mfma_f32_32x32x16_f16 v[50:65], v[180:183], v[86:89], v[50:65]
	v_mfma_f32_32x32x16_f16 v[34:49], v[168:171], v[66:69], v[34:49]
	v_mfma_f32_32x32x16_f16 v[50:65], v[184:187], v[66:69], v[50:65]
	v_mfma_f32_32x32x16_f16 v[34:49], v[172:175], v[70:73], v[34:49]
	v_mfma_f32_32x32x16_f16 v[50:65], v[188:191], v[70:73], v[50:65]
	s_cmp_gt_u32 s1, 57
	s_cselect_b64 s[30:31], -1, 0
	s_and_b64 vcc, exec, s[30:31]
	s_cbranch_vccnz .LBB0_635
	s_mul_i32 s3, s0, 0xab
	s_bfe_u32 s3, s3, 0x6000a
	s_mul_i32 s3, s3, 6
	s_sub_i32 s3, s0, s3
	s_and_b32 s3, s3, 0xff
	s_mulk_i32 s3, 0x3000
	s_add_i32 s3, s3, 0
	s_mov_b64 s[36:37], 0x30000
	v_lshl_add_u64 v[66:67], v[158:159], 0, s[36:37]
	s_mov_b32 m0, s3
	s_mov_b64 s[28:29], 0x30400
	global_load_lds_dwordx4 v[66:67], off nt
	v_lshl_add_u64 v[66:67], v[158:159], 0, s[28:29]
	s_add_i32 m0, s3, 0x400
	s_mov_b64 s[28:29], 0x30800
	global_load_lds_dwordx4 v[66:67], off nt
	v_lshl_add_u64 v[66:67], v[158:159], 0, s[28:29]
	s_add_i32 m0, s3, 0x800
	s_mov_b64 s[28:29], 0x30c00
	global_load_lds_dwordx4 v[66:67], off nt
	v_lshl_add_u64 v[66:67], v[158:159], 0, s[28:29]
	s_add_i32 m0, s3, 0xc00
	s_mov_b64 s[28:29], 0x34000
	global_load_lds_dwordx4 v[66:67], off nt
	v_lshl_add_u64 v[66:67], v[156:157], 0, s[36:37]
	s_add_i32 m0, s3, 0x1000
	s_nop 0
	global_load_lds_dwordx4 v[66:67], off nt
	v_lshl_add_u64 v[66:67], v[154:155], 0, s[36:37]
	s_add_i32 m0, s3, 0x1400
	s_nop 0
	global_load_lds_dwordx4 v[66:67], off nt
	v_lshl_add_u64 v[66:67], v[152:153], 0, s[36:37]
	s_add_i32 m0, s3, 0x1800
	s_nop 0
	global_load_lds_dwordx4 v[66:67], off nt
	v_lshl_add_u64 v[66:67], v[150:151], 0, s[36:37]
	s_add_i32 m0, s3, 0x1c00
	s_mov_b64 s[36:37], 0x34010
	global_load_lds_dwordx4 v[66:67], off nt
	v_lshl_add_u64 v[66:67], v[148:149], 0, s[28:29]
	s_add_i32 m0, s3, 0x2000
	s_nop 0
	global_load_lds_dwordx4 v[66:67], off nt
	v_lshl_add_u64 v[66:67], v[148:149], 0, s[36:37]
	s_add_i32 m0, s3, 0x2400
	s_nop 0
	global_load_lds_dwordx4 v[66:67], off nt
	v_lshl_add_u64 v[66:67], v[144:145], 0, s[28:29]
	s_add_i32 m0, s3, 0x2800
	s_nop 0
	global_load_lds_dwordx4 v[66:67], off nt
	v_lshl_add_u64 v[66:67], v[144:145], 0, s[36:37]
	s_add_i32 m0, s3, 0x2c00
	s_nop 0
	global_load_lds_dwordx4 v[66:67], off nt
